# HGRN blocks: logf expansion trimmed to its live path (normal finite argument), pass-3 prefetch through persistent 32-bit offsets instead of 64-bit multiply-adds
# speedup vs baseline: 1.0669x; 1.0066x over previous
.LBB0_75:
	v_mov_b32_e32 v43, 0
	v_log_f32_e32 v36, v83
	s_nop 0
	v_mul_f32_e32 v37, 0x3f317217, v36
	v_fma_f32 v37, v36, s97, -v37
	v_fmac_f32_e32 v37, 0x3377d1cf, v36
	v_fmac_f32_e32 v37, 0x3f317217, v36
	v_mov_b32_e32 v36, v37
	v_add_f32_e32 v80, 0, v36
	v_log_f32_e32 v37, v82
	s_nop 0
	v_mul_f32_e32 v36, 0x3f317217, v37
	v_fma_f32 v36, v37, s97, -v36
	v_fmac_f32_e32 v36, 0x3377d1cf, v37
	v_fmac_f32_e32 v36, 0x3f317217, v37
	v_log_f32_e32 v37, v81
	v_add_f32_e32 v81, v36, v80
	v_mul_f32_e32 v36, 0x3f317217, v37
	v_fma_f32 v36, v37, s97, -v36
	v_fmac_f32_e32 v36, 0x3377d1cf, v37
	v_fmac_f32_e32 v36, 0x3f317217, v37
	v_log_f32_e32 v37, v79
	v_add_f32_e32 v79, v36, v81
	v_mul_f32_e32 v36, 0x3f317217, v37
	v_fma_f32 v36, v37, s97, -v36
	v_fmac_f32_e32 v36, 0x3377d1cf, v37
	v_fmac_f32_e32 v36, 0x3f317217, v37
	v_add_f32_e32 v37, v36, v79
	ds_write_b32 v63, v37 offset:21504
	s_waitcnt lgkmcnt(0)
	s_barrier
	ds_read2st64_b32 v[38:39], v62 offset0:84 offset1:86
	ds_read2st64_b32 v[40:41], v62 offset0:88 offset1:90
	s_and_saveexec_b64 s[4:5], s[40:41]
	s_cbranch_execz .LBB0_83
	v_cmp_lt_i32_e64 s[0:1], 1, v60
	s_mov_b64 s[6:7], 0
	s_and_saveexec_b64 s[8:9], s[0:1]
	s_xor_b64 s[8:9], exec, s[8:9]
	s_cbranch_execz .LBB0_131
	v_cmp_eq_u32_e64 s[0:1], 2, v60
	s_mov_b64 s[6:7], -1
	s_and_saveexec_b64 s[10:11], s[0:1]
	s_cbranch_execz .LBB0_79
	s_waitcnt lgkmcnt(0)
	v_add_f32_e32 v43, v38, v39
	s_xor_b64 s[6:7], exec, -1

.LBB0_85:
	s_or_b64 exec, exec, s[0:1]
	v_add_u32_e32 v81, s15, v75
	v_add_u32_e32 v38, 32, v81
	v_mad_i64_i32 v[36:37], s[0:1], v38, s96, v[56:57]
	global_load_dword v50, v[36:37], off
	v_mad_i64_i32 v[36:37], s[0:1], v38, s30, v[58:59]
	v_add_u32_e32 v38, 33, v81
	global_load_ushort v77, v[36:37], off
	v_mad_i64_i32 v[36:37], s[0:1], v38, s96, v[56:57]
	global_load_dword v51, v[36:37], off
	v_mad_i64_i32 v[36:37], s[0:1], v38, s30, v[58:59]
	v_add_u32_e32 v38, 34, v81
	global_load_ushort v79, v[36:37], off
	v_mad_i64_i32 v[36:37], s[0:1], v38, s96, v[56:57]
	global_load_dword v52, v[36:37], off
	v_mad_i64_i32 v[36:37], s[0:1], v38, s30, v[58:59]
	v_add_u32_e32 v38, 35, v81
	global_load_ushort v78, v[36:37], off
	v_mad_i64_i32 v[36:37], s[0:1], v38, s96, v[56:57]
	global_load_dword v53, v[36:37], off
	v_mad_i64_i32 v[36:37], s[0:1], v38, s30, v[58:59]
	global_load_ushort v80, v[36:37], off
	s_waitcnt lgkmcnt(0)
	s_barrier
	ds_read_b64 v[238:239], v160 offset:14848
	ds_read_b64 v[222:223], v161 offset:8704
	ds_read_b128 v[190:193], v55 offset:20992
	ds_read_b64 v[224:225], v161 offset:9472
	ds_read_b128 v[194:197], v55 offset:21056
	ds_read_b64 v[226:227], v161 offset:10240
	ds_read_b128 v[198:201], v55 offset:21120
	ds_read_b64 v[228:229], v161 offset:11008
	ds_read_b128 v[202:205], v55 offset:21184
	ds_read_b64 v[230:231], v161 offset:11776
	ds_read_b128 v[206:209], v55 offset:21248
	ds_read_b64 v[232:233], v161 offset:12544
	ds_read_b128 v[210:213], v55 offset:21312
	s_waitcnt lgkmcnt(10)
	v_pk_mul_f32 v[34:35], v[34:35], v[192:193]
	v_pk_mul_f32 v[32:33], v[32:33], v[190:191]
	s_nop 1
	v_mfma_f32_16x16x16_bf16 v[32:35], v[222:223], v[238:239], v[32:35]
	ds_read_b64 v[234:235], v161 offset:13312
	ds_read_b128 v[214:217], v55 offset:21376
	s_waitcnt lgkmcnt(10)
	v_pk_mul_f32 v[30:31], v[30:31], v[196:197]
	v_pk_mul_f32 v[28:29], v[28:29], v[194:195]
	s_nop 1
	v_mfma_f32_16x16x16_bf16 v[28:31], v[224:225], v[238:239], v[28:31]
	ds_read_b64 v[236:237], v161 offset:14080
	ds_read_b128 v[218:221], v55 offset:21440
	s_waitcnt lgkmcnt(10)
	v_pk_mul_f32 v[26:27], v[26:27], v[200:201]
	v_pk_mul_f32 v[24:25], v[24:25], v[198:199]
	s_nop 1
	v_mfma_f32_16x16x16_bf16 v[24:27], v[226:227], v[238:239], v[24:27]
	s_waitcnt lgkmcnt(8)
	v_pk_mul_f32 v[22:23], v[22:23], v[204:205]
	v_pk_mul_f32 v[20:21], v[20:21], v[202:203]
	s_nop 1
	v_mfma_f32_16x16x16_bf16 v[20:23], v[228:229], v[238:239], v[20:23]
	s_waitcnt lgkmcnt(6)
	v_pk_mul_f32 v[18:19], v[18:19], v[208:209]
	v_pk_mul_f32 v[16:17], v[16:17], v[206:207]
	s_nop 1
	v_mfma_f32_16x16x16_bf16 v[16:19], v[230:231], v[238:239], v[16:19]
	s_waitcnt lgkmcnt(4)
	v_pk_mul_f32 v[14:15], v[14:15], v[212:213]
	v_pk_mul_f32 v[12:13], v[12:13], v[210:211]
	s_nop 1
	v_mfma_f32_16x16x16_bf16 v[12:15], v[232:233], v[238:239], v[12:15]
	s_waitcnt lgkmcnt(2)
	v_pk_mul_f32 v[10:11], v[10:11], v[216:217]
	v_pk_mul_f32 v[8:9], v[8:9], v[214:215]
	s_nop 1
	v_mfma_f32_16x16x16_bf16 v[8:11], v[234:235], v[238:239], v[8:11]
	s_waitcnt vmcnt(8)
	v_sub_f32_e32 v36, 1.0, v46
	v_max_f32_e32 v76, 0xda24260, v36
	v_sub_f32_e32 v36, 1.0, v47
	v_max_f32_e32 v74, 0xda24260, v36
	v_sub_f32_e32 v36, 1.0, v48
	v_max_f32_e32 v73, 0xda24260, v36
	v_sub_f32_e32 v36, 1.0, v49
	v_max_f32_e32 v72, 0xda24260, v36
	v_mov_b32_e32 v64, v162
	v_mov_b32_e32 v66, v163
	v_mov_b32_e32 v65, v164
	v_mov_b32_e32 v67, v165
	s_waitcnt lgkmcnt(0)
	s_barrier
	v_pk_mul_f32 v[6:7], v[6:7], v[220:221]
	v_pk_mul_f32 v[4:5], v[4:5], v[218:219]
	s_nop 1
	v_mfma_f32_16x16x16_bf16 v[4:7], v[236:237], v[238:239], v[4:7]
	v_log_f32_e32 v36, v76
	s_nop 0
	v_mul_f32_e32 v37, 0x3f317217, v36
	v_fma_f32 v37, v36, s97, -v37
	v_fmac_f32_e32 v37, 0x3377d1cf, v36
	v_fmac_f32_e32 v37, 0x3f317217, v36
	v_mov_b32_e32 v36, v37
	v_add_f32_e32 v42, 0, v36
	v_log_f32_e32 v36, v74
	s_nop 0
	v_mul_f32_e32 v37, 0x3f317217, v36
	v_fma_f32 v37, v36, s97, -v37
	v_fmac_f32_e32 v37, 0x3377d1cf, v36
	v_fmac_f32_e32 v37, 0x3f317217, v36
	v_mov_b32_e32 v36, v37
	v_add_f32_e32 v43, v36, v42
	v_log_f32_e32 v36, v73
	s_nop 0
	v_mul_f32_e32 v37, 0x3f317217, v36
	v_fma_f32 v37, v36, s97, -v37
	v_fmac_f32_e32 v37, 0x3377d1cf, v36
	v_fmac_f32_e32 v37, 0x3f317217, v36
	v_mov_b32_e32 v36, v37
	v_add_f32_e32 v73, v36, v43
	v_log_f32_e32 v36, v72
	s_nop 0
	v_mul_f32_e32 v37, 0x3f317217, v36
	v_fma_f32 v37, v36, s97, -v37
	v_fmac_f32_e32 v37, 0x3377d1cf, v36
	v_fmac_f32_e32 v37, 0x3f317217, v36
	v_mov_b32_e32 v36, v37
	v_add_f32_e32 v37, v36, v73
	ds_write_b32 v63, v37 offset:21504
	s_waitcnt lgkmcnt(0)
	s_barrier
	ds_read2st64_b32 v[38:39], v62 offset0:84 offset1:86
	ds_read2st64_b32 v[40:41], v62 offset0:88 offset1:90
	s_and_saveexec_b64 s[4:5], s[40:41]
	s_cbranch_execz .LBB0_111
	v_cmp_lt_i32_e64 s[0:1], 1, v60
	s_mov_b64 s[6:7], 0
	s_and_saveexec_b64 s[8:9], s[0:1]
	s_xor_b64 s[8:9], exec, s[8:9]
	s_cbranch_execz .LBB0_133
	v_cmp_eq_u32_e64 s[0:1], 2, v60
	s_mov_b64 s[6:7], -1
	s_and_saveexec_b64 s[10:11], s[0:1]
	s_cbranch_execz .LBB0_107
	s_waitcnt lgkmcnt(1)
	v_add_f32_e32 v45, v38, v39
	s_xor_b64 s[6:7], exec, -1

.LBB0_135:
	v_mov_b32_e32 v43, 0
	v_log_f32_e32 v36, v83
	s_nop 0
	v_mul_f32_e32 v37, 0x3f317217, v36
	v_fma_f32 v37, v36, s97, -v37
	v_fmac_f32_e32 v37, 0x3377d1cf, v36
	v_fmac_f32_e32 v37, 0x3f317217, v36
	v_mov_b32_e32 v36, v37
	v_add_f32_e32 v56, 0, v36
	v_log_f32_e32 v37, v82
	s_nop 0
	v_mul_f32_e32 v36, 0x3f317217, v37
	v_fma_f32 v36, v37, s97, -v36
	v_fmac_f32_e32 v36, 0x3377d1cf, v37
	v_fmac_f32_e32 v36, 0x3f317217, v37
	v_add_f32_e32 v57, v56, v36
	v_log_f32_e32 v37, v81
	s_nop 0
	v_mul_f32_e32 v36, 0x3f317217, v37
	v_fma_f32 v36, v37, s97, -v36
	v_fmac_f32_e32 v36, 0x3377d1cf, v37
	v_fmac_f32_e32 v36, 0x3f317217, v37
	v_add_f32_e32 v58, v57, v36
	v_log_f32_e32 v37, v79
	s_nop 0
	v_mul_f32_e32 v36, 0x3f317217, v37
	v_fma_f32 v36, v37, s97, -v36
	v_fmac_f32_e32 v36, 0x3377d1cf, v37
	v_fmac_f32_e32 v36, 0x3f317217, v37
	v_add_f32_e32 v37, v58, v36
	ds_write_b32 v63, v37 offset:21504
	s_waitcnt lgkmcnt(0)
	s_barrier
	ds_read2st64_b32 v[38:39], v62 offset0:84 offset1:86
	ds_read2st64_b32 v[40:41], v62 offset0:88 offset1:90
	s_and_saveexec_b64 s[4:5], s[40:41]
	s_cbranch_execz .LBB0_143
	v_cmp_lt_i32_e64 s[0:1], 1, v60
	s_mov_b64 s[6:7], 0
	s_and_saveexec_b64 s[8:9], s[0:1]
	s_xor_b64 s[8:9], exec, s[8:9]
	s_cbranch_execz .LBB0_193
	v_cmp_eq_u32_e64 s[0:1], 2, v60
	s_mov_b64 s[6:7], -1
	s_and_saveexec_b64 s[10:11], s[0:1]
	s_cbranch_execz .LBB0_139
	s_waitcnt lgkmcnt(1)
	v_add_f32_e32 v43, v38, v39
	s_xor_b64 s[6:7], exec, -1

.LBB0_145:
	s_or_b64 exec, exec, s[0:1]
	s_waitcnt lgkmcnt(0)
	s_barrier
	ds_read_b64 v[238:239], v160 offset:14848
	ds_read_b64 v[222:223], v161 offset:8704
	ds_read_b128 v[190:193], v55 offset:20992
	ds_read_b64 v[224:225], v161 offset:9472
	ds_read_b128 v[194:197], v55 offset:21056
	ds_read_b64 v[226:227], v161 offset:10240
	ds_read_b128 v[198:201], v55 offset:21120
	ds_read_b64 v[228:229], v161 offset:11008
	ds_read_b128 v[202:205], v55 offset:21184
	ds_read_b64 v[230:231], v161 offset:11776
	ds_read_b128 v[206:209], v55 offset:21248
	ds_read_b64 v[232:233], v161 offset:12544
	ds_read_b128 v[210:213], v55 offset:21312
	s_waitcnt lgkmcnt(10)
	v_pk_mul_f32 v[34:35], v[34:35], v[192:193]
	v_pk_mul_f32 v[32:33], v[32:33], v[190:191]
	s_nop 1
	v_mfma_f32_16x16x16_bf16 v[32:35], v[222:223], v[238:239], v[32:35]
	ds_read_b64 v[234:235], v161 offset:13312
	ds_read_b128 v[214:217], v55 offset:21376
	s_waitcnt lgkmcnt(10)
	v_pk_mul_f32 v[30:31], v[30:31], v[196:197]
	v_pk_mul_f32 v[28:29], v[28:29], v[194:195]
	s_nop 1
	v_mfma_f32_16x16x16_bf16 v[28:31], v[224:225], v[238:239], v[28:31]
	ds_read_b64 v[236:237], v161 offset:14080
	ds_read_b128 v[218:221], v55 offset:21440
	s_waitcnt lgkmcnt(10)
	v_pk_mul_f32 v[26:27], v[26:27], v[200:201]
	v_pk_mul_f32 v[24:25], v[24:25], v[198:199]
	s_nop 1
	v_mfma_f32_16x16x16_bf16 v[24:27], v[226:227], v[238:239], v[24:27]
	s_waitcnt lgkmcnt(8)
	v_pk_mul_f32 v[22:23], v[22:23], v[204:205]
	v_pk_mul_f32 v[20:21], v[20:21], v[202:203]
	s_nop 1
	v_mfma_f32_16x16x16_bf16 v[20:23], v[228:229], v[238:239], v[20:23]
	s_waitcnt lgkmcnt(6)
	v_pk_mul_f32 v[18:19], v[18:19], v[208:209]
	v_pk_mul_f32 v[16:17], v[16:17], v[206:207]
	s_nop 1
	v_mfma_f32_16x16x16_bf16 v[16:19], v[230:231], v[238:239], v[16:19]
	s_waitcnt lgkmcnt(4)
	v_pk_mul_f32 v[14:15], v[14:15], v[212:213]
	v_pk_mul_f32 v[12:13], v[12:13], v[210:211]
	s_nop 1
	v_mfma_f32_16x16x16_bf16 v[12:15], v[232:233], v[238:239], v[12:15]
	s_waitcnt lgkmcnt(2)
	v_pk_mul_f32 v[10:11], v[10:11], v[216:217]
	v_pk_mul_f32 v[8:9], v[8:9], v[214:215]
	s_nop 1
	v_mfma_f32_16x16x16_bf16 v[8:11], v[234:235], v[238:239], v[8:11]
	s_waitcnt vmcnt(0)
	v_sub_f32_e32 v36, 1.0, v46
	v_max_f32_e32 v76, 0xda24260, v36
	v_sub_f32_e32 v36, 1.0, v47
	v_max_f32_e32 v74, 0xda24260, v36
	v_sub_f32_e32 v36, 1.0, v48
	v_max_f32_e32 v73, 0xda24260, v36
	v_sub_f32_e32 v36, 1.0, v49
	v_max_f32_e32 v72, 0xda24260, v36
	v_mov_b32_e32 v64, v162
	v_mov_b32_e32 v66, v163
	v_mov_b32_e32 v65, v164
	v_mov_b32_e32 v67, v165
	s_waitcnt lgkmcnt(0)
	s_barrier
	v_pk_mul_f32 v[6:7], v[6:7], v[220:221]
	v_pk_mul_f32 v[4:5], v[4:5], v[218:219]
	s_nop 1
	v_mfma_f32_16x16x16_bf16 v[4:7], v[236:237], v[238:239], v[4:7]
	v_log_f32_e32 v36, v76
	s_nop 0
	v_mul_f32_e32 v37, 0x3f317217, v36
	v_fma_f32 v37, v36, s97, -v37
	v_fmac_f32_e32 v37, 0x3377d1cf, v36
	v_fmac_f32_e32 v37, 0x3f317217, v36
	v_mov_b32_e32 v36, v37
	v_add_f32_e32 v42, 0, v36
	v_log_f32_e32 v36, v74
	s_nop 0
	v_mul_f32_e32 v37, 0x3f317217, v36
	v_fma_f32 v37, v36, s97, -v37
	v_fmac_f32_e32 v37, 0x3377d1cf, v36
	v_fmac_f32_e32 v37, 0x3f317217, v36
	v_mov_b32_e32 v36, v37
	v_add_f32_e32 v43, v42, v36
	v_log_f32_e32 v36, v73
	s_nop 0
	v_mul_f32_e32 v37, 0x3f317217, v36
	v_fma_f32 v37, v36, s97, -v37
	v_fmac_f32_e32 v37, 0x3377d1cf, v36
	v_fmac_f32_e32 v37, 0x3f317217, v36
	v_mov_b32_e32 v36, v37
	v_add_f32_e32 v53, v43, v36
	v_log_f32_e32 v36, v72
	s_nop 0
	v_mul_f32_e32 v37, 0x3f317217, v36
	v_fma_f32 v37, v36, s97, -v37
	v_fmac_f32_e32 v37, 0x3377d1cf, v36
	v_fmac_f32_e32 v37, 0x3f317217, v36
	v_mov_b32_e32 v36, v37
	v_add_f32_e32 v37, v53, v36
	ds_write_b32 v63, v37 offset:21504
	s_waitcnt lgkmcnt(0)
	s_barrier
	ds_read2st64_b32 v[38:39], v62 offset0:84 offset1:86
	ds_read2st64_b32 v[40:41], v62 offset0:88 offset1:90
	s_and_saveexec_b64 s[4:5], s[40:41]
	s_cbranch_execz .LBB0_171
	v_cmp_lt_i32_e64 s[0:1], 1, v60
	s_mov_b64 s[6:7], 0
	s_and_saveexec_b64 s[8:9], s[0:1]
	s_xor_b64 s[8:9], exec, s[8:9]
	s_cbranch_execz .LBB0_195
	v_cmp_eq_u32_e64 s[0:1], 2, v60
	s_mov_b64 s[6:7], -1
	s_and_saveexec_b64 s[10:11], s[0:1]
	s_cbranch_execz .LBB0_167
	s_waitcnt lgkmcnt(1)
	v_add_f32_e32 v45, v38, v39
	s_xor_b64 s[6:7], exec, -1

.LBB0_349:
	s_ashr_i32 s52, s18, 5
	s_lshl_b32 s6, s19, 8
	s_lshl_b32 s10, s52, 11
	v_ashrrev_i32_e32 v83, 7, v3
	s_and_b32 s7, s8, 3
	s_or_b32 s6, s6, s10
	v_lshlrev_b32_e32 v78, 2, v83
	s_lshl_b32 s1, s9, 8
	v_and_b32_e32 v0, 0x7f, v3
	v_add_u32_e32 v1, s6, v78
	s_lshl_b32 s6, s7, 8
	v_lshl_or_b32 v4, s7, 7, v0
	s_add_u32 s8, s80, s6
	v_lshlrev_b32_e32 v50, 1, v4
	v_lshlrev_b32_e32 v52, 2, v4
	s_addc_u32 s9, s81, 0
	s_mov_b64 s[56:57], s[8:9]
	v_add_u32_e32 v240, 32, v1
	v_mul_lo_u32 v244, v240, s30
	v_mul_lo_u32 v240, v240, s96
	v_lshl_add_u32 v244, v0, 1, v244
	v_add_u32_e32 v242, v240, v50
	v_add_u32_e32 v242, 0x800, v242
	v_add_u32_e32 v240, v240, v52
	v_add_u32_e32 v241, 0x1800, v240
	v_add_u32_e32 v243, 0x1800, v242
	v_add_u32_e32 v245, 0x2600, v244
	v_add_u32_e32 v246, 0x4c00, v244
	v_add_u32_e32 v247, 0x7200, v244
	v_lshlrev_b32_e32 v4, 1, v0
	v_mov_b32_e32 v5, v2
	v_lshl_add_u64 v[54:55], s[8:9], 0, v[4:5]
	v_mov_b64_e32 v[4:5], s[82:83]
	v_or_b32_e32 v56, 1, v1
	v_or_b32_e32 v66, 2, v1
	v_mov_b32_e32 v51, v2
	v_mov_b32_e32 v53, v2
	v_mad_i64_i32 v[6:7], s[12:13], v1, s96, v[4:5]
	v_mad_i64_i32 v[46:47], s[12:13], v56, s96, v[4:5]
	v_mad_i64_i32 v[58:59], s[12:13], v56, s30, v[54:55]
	v_mad_i64_i32 v[56:57], s[12:13], v66, s96, v[4:5]
	v_lshl_add_u64 v[42:43], v[6:7], 0, v[50:51]
	v_lshl_add_u64 v[6:7], v[6:7], 0, v[52:53]
	v_lshl_add_u64 v[48:49], v[46:47], 0, v[50:51]
	v_lshl_add_u64 v[60:61], v[56:57], 0, v[52:53]
	v_mad_i64_i32 v[44:45], s[12:13], v1, s30, v[54:55]
	v_lshl_add_u64 v[46:47], v[46:47], 0, v[52:53]
	v_lshl_add_u64 v[62:63], v[56:57], 0, v[50:51]
	global_load_dword v56, v[6:7], off
	global_load_ushort v84, v[44:45], off
	global_load_ushort v67, v[48:49], off offset:2048
	global_load_dword v57, v[46:47], off
	s_waitcnt lgkmcnt(0)
	global_load_ushort v85, v[58:59], off
	s_nop 0
	global_load_dword v60, v[60:61], off
	s_nop 0
	global_load_ushort v68, v[62:63], off offset:2048
	global_load_ushort v69, v[42:43], off offset:2048
	v_or_b32_e32 v70, 3, v1
	v_add_u32_e32 v48, 16, v1
	v_mad_i64_i32 v[6:7], s[12:13], v70, s96, v[4:5]
	v_mad_i64_i32 v[44:45], s[12:13], v48, s96, v[4:5]
	v_add_u32_e32 v71, 17, v1
	v_lshl_add_u64 v[42:43], v[6:7], 0, v[50:51]
	v_lshl_add_u64 v[46:47], v[44:45], 0, v[50:51]
	v_mad_i64_i32 v[62:63], s[12:13], v71, s96, v[4:5]
	v_lshl_add_u64 v[6:7], v[6:7], 0, v[52:53]
	v_lshl_add_u64 v[44:45], v[44:45], 0, v[52:53]
	v_mad_i64_i32 v[48:49], s[12:13], v48, s30, v[54:55]
	v_lshl_add_u64 v[64:65], v[62:63], 0, v[50:51]
	global_load_ushort v72, v[42:43], off offset:2048
	global_load_dword v61, v[6:7], off
	global_load_dword v58, v[44:45], off
	global_load_ushort v86, v[48:49], off
	global_load_ushort v74, v[64:65], off offset:2048
	global_load_ushort v75, v[46:47], off offset:2048
	v_add_u32_e32 v46, 18, v1
	v_add_u32_e32 v1, 19, v1
	v_mad_i64_i32 v[42:43], s[12:13], v46, s96, v[4:5]
	v_mad_i64_i32 v[4:5], s[12:13], v1, s96, v[4:5]
	v_lshl_add_u64 v[6:7], v[62:63], 0, v[52:53]
	v_lshl_add_u64 v[44:45], v[42:43], 0, v[50:51]
	v_lshl_add_u64 v[48:49], v[4:5], 0, v[50:51]
	v_lshl_add_u64 v[4:5], v[4:5], 0, v[52:53]
	v_lshl_add_u64 v[42:43], v[42:43], 0, v[52:53]
	v_mad_i64_i32 v[46:47], s[12:13], v46, s30, v[54:55]
	v_mad_i64_i32 v[64:65], s[12:13], v1, s30, v[54:55]
	global_load_dword v59, v[6:7], off
	global_load_dword v62, v[42:43], off
	global_load_ushort v98, v[46:47], off
	global_load_ushort v1, v[48:49], off offset:2048
	global_load_dword v63, v[4:5], off
	s_waitcnt lgkmcnt(0)
	global_load_ushort v101, v[64:65], off
	s_nop 0
	global_load_ushort v44, v[44:45], off offset:2048
	v_mad_i64_i32 v[4:5], s[12:13], v66, s30, v[54:55]
	v_mad_i64_i32 v[6:7], s[12:13], v70, s30, v[54:55]
	v_readlane_b32 s11, v254, 59
	global_load_ushort v108, v[6:7], off
	global_load_ushort v107, v[4:5], off
	v_mov_b32_e32 v4, s11
	ds_read_b64 v[4:5], v4
	v_mad_i64_i32 v[6:7], s[12:13], v71, s30, v[54:55]
	v_lshlrev_b32_e32 v45, 2, v3
	v_and_b32_e32 v46, 0x7c, v45
	s_waitcnt lgkmcnt(0)
	v_readfirstlane_b32 s11, v4
	v_readfirstlane_b32 s12, v5
	s_add_u32 s11, s11, s4
	s_addc_u32 s13, s12, s5
	s_lshl_b32 s12, s7, 9
	s_add_u32 s12, s11, s12
	s_addc_u32 s13, s13, 0
	v_lshlrev_b32_e32 v42, 2, v46
	v_mov_b32_e32 v43, v2
	v_lshl_add_u64 v[4:5], s[12:13], 0, v[42:43]
	global_load_ushort v89, v[6:7], off
	v_and_b32_e32 v87, 15, v3
	flat_load_dwordx4 v[4:7], v[4:5]
	s_add_u32 s12, s62, s6
	s_movk_i32 s6, 0x80
	s_addc_u32 s13, s63, 0
	v_cmp_gt_u32_e64 s[38:39], s6, v3
	s_lshl_b32 s6, s0, 4
	v_add_u32_e32 v88, 0, v45
	v_add_u32_e32 v45, 0, v42
	v_lshlrev_b32_e32 v42, 1, v46
	s_lshl_b32 s0, s0, 6
	v_lshlrev_b32_e32 v49, 2, v82
	v_lshl_add_u32 v91, v0, 2, 0
	v_cmp_gt_u32_e64 s[42:43], 32, v40
	v_mad_u32_u24 v46, v0, 44, v91
	v_mul_i32_i24_e32 v47, 0xffffffd4, v0
	s_waitcnt vmcnt(0)
	v_sub_f32_e32 v43, 1.0, v56
	v_max_f32_e32 v109, 0xda24260, v43
	v_mov_b32_e32 v166, v67
	v_sub_f32_e32 v43, 1.0, v57
	v_max_f32_e32 v110, 0xda24260, v43
	v_sub_f32_e32 v43, 1.0, v60
	v_max_f32_e32 v111, 0xda24260, v43
	v_and_b32_e32 v96, 48, v3
	v_cmp_lt_u32_e64 s[40:41], s51, v3
	v_or_b32_e32 v90, 2, v82
	v_mov_b32_e32 v167, v69
	v_mov_b32_e32 v169, v68
	v_lshl_add_u32 v92, v83, 3, v46
	v_add_u32_e32 v97, 0, v49
	v_cmp_gt_u32_e64 s[44:45], v82, v87
	v_cmp_lt_u32_e64 s[46:47], v82, v87
	v_cmp_gt_u32_e64 s[48:49], v90, v87
	s_mov_b32 s53, 0
	v_add_u32_e32 v104, v46, v47
	v_mov_b32_e32 v168, v72
	v_sub_f32_e32 v43, 1.0, v61
	v_max_f32_e32 v113, 0xda24260, v43
	v_sub_f32_e32 v43, 1.0, v58
	v_max_f32_e32 v112, 0xda24260, v43
	v_mov_b32_e32 v171, v75
	v_mov_b32_e32 v170, v74
	s_mov_b32 s54, 0
	v_sub_f32_e32 v43, 1.0, v59
	v_max_f32_e32 v114, 0xda24260, v43
	v_sub_f32_e32 v43, 1.0, v62
	v_mov_b32_e32 v172, v1
	v_sub_f32_e32 v1, 1.0, v63
	v_max_f32_e32 v116, 0xda24260, v1
	v_mul_u32_u24_e32 v1, 0x88, v87
	v_max_f32_e32 v115, 0xda24260, v43
	v_mov_b32_e32 v43, v2
	v_lshl_add_u32 v48, v1, 1, 0
	v_or_b32_e32 v1, s6, v87
	v_lshl_add_u64 v[64:65], s[12:13], 0, v[42:43]
	v_mad_u64_u32 v[66:67], s[12:13], v1, 48, v[2:3]
	v_lshl_add_u32 v1, v87, 8, v48
	v_mov_b32_e32 v173, v44
	v_ashrrev_i32_e32 v44, 5, v3
	v_add3_u32 v95, v1, s0, v49
	s_movk_i32 s0, 0x210
	v_mul_lo_u32 v40, v44, s0
	s_movk_i32 s0, 0x220
	v_mad_u64_u32 v[0:1], s[12:13], v83, s0, v[0:1]
	v_lshl_add_u32 v93, v41, 4, v48
	v_lshlrev_b32_e32 v41, 1, v82
	v_add_u32_e32 v3, 0, v96
	v_lshl_add_u32 v99, v0, 1, 0
	v_or_b32_e32 v67, 3, v82
	v_mul_u32_u24_e32 v0, 48, v87
	s_or_b32 s0, s10, s1
	v_add_u32_e32 v94, v66, v41
	v_add_u32_e32 v100, v48, v41
	v_cmp_gt_u32_e64 s[50:51], v67, v87
	v_lshl_add_u64 v[68:69], s[8:9], 0, v[42:43]
	v_add_u32_e32 v102, s0, v78
	v_add_u32_e32 v103, s0, v44
	v_add_u32_e32 v105, v3, v0
	v_add_u32_e32 v106, v45, v40
	v_lshrrev_b32_e32 v174, 1, v96
	v_sub_u32_e32 v175, v105, v174
	v_add_u32_e32 v174, v66, v174
	s_branch .LBB0_351

.LBB0_351:
	v_add_u32_e32 v78, s53, v103
	v_mad_i64_i32 v[0:1], s[0:1], v78, s30, v[68:69]
	global_load_dwordx2 v[80:81], v[0:1], off offset:1024
	v_sub_f32_e32 v0, 1.0, v56
	v_max_f32_e32 v109, 0xda24260, v0
	v_sub_f32_e32 v0, 1.0, v57
	v_max_f32_e32 v110, 0xda24260, v0
	v_sub_f32_e32 v0, 1.0, v60
	v_max_f32_e32 v111, 0xda24260, v0
	v_sub_f32_e32 v0, 1.0, v61
	v_max_f32_e32 v113, 0xda24260, v0
	v_lshlrev_b32_e32 v70, 16, v166
	v_lshlrev_b32_e32 v71, 16, v167
	v_lshlrev_b32_e32 v72, 16, v168
	v_lshlrev_b32_e32 v73, 16, v169
	v_mov_b32_e32 v41, 0
	v_log_f32_e32 v0, v109
	s_nop 0
	v_mul_f32_e32 v1, 0x3f317217, v0
	v_fma_f32 v1, v0, s97, -v1
	v_fmac_f32_e32 v1, 0x3377d1cf, v0
	v_fmac_f32_e32 v1, 0x3f317217, v0
	v_mov_b32_e32 v0, v1
	v_add_f32_e32 v47, 0, v0
	v_log_f32_e32 v1, v110
	s_nop 0
	v_mul_f32_e32 v0, 0x3f317217, v1
	v_fma_f32 v0, v1, s97, -v0
	v_fmac_f32_e32 v0, 0x3377d1cf, v1
	v_fmac_f32_e32 v0, 0x3f317217, v1
	v_add_f32_e32 v46, v0, v47
	v_log_f32_e32 v1, v111
	s_nop 0
	v_mul_f32_e32 v0, 0x3f317217, v1
	v_fma_f32 v0, v1, s97, -v0
	v_fmac_f32_e32 v0, 0x3377d1cf, v1
	v_fmac_f32_e32 v0, 0x3f317217, v1
	v_add_f32_e32 v3, v0, v46
	v_log_f32_e32 v1, v113
	s_nop 0
	v_mul_f32_e32 v0, 0x3f317217, v1
	v_fma_f32 v0, v1, s97, -v0
	v_fmac_f32_e32 v0, 0x3377d1cf, v1
	v_fmac_f32_e32 v0, 0x3f317217, v1
	v_add_f32_e32 v1, v0, v3
	ds_write_b32 v88, v1 offset:21504
	s_waitcnt lgkmcnt(0)
	s_barrier
	ds_read2st64_b32 v[42:43], v91 offset0:84 offset1:86
	ds_read2st64_b32 v[44:45], v91 offset0:88 offset1:90
	s_and_saveexec_b64 s[0:1], s[40:41]
	s_cbranch_execz .LBB0_359
	v_cmp_lt_i32_e32 vcc, 1, v83
	s_mov_b64 s[8:9], 0
	s_and_saveexec_b64 s[10:11], vcc
	s_xor_b64 s[10:11], exec, s[10:11]
	s_cbranch_execz .LBB0_411
	v_cmp_eq_u32_e32 vcc, 2, v83
	s_mov_b64 s[8:9], -1
	s_and_saveexec_b64 s[12:13], vcc
	s_cbranch_execz .LBB0_355
	s_waitcnt lgkmcnt(0)
	v_add_f32_e32 v41, v42, v43
	s_xor_b64 s[8:9], exec, -1

.LBB0_361:
	s_or_b64 exec, exec, s[0:1]
	s_cmp_lt_u32 s54, 7
	s_cselect_b64 s[8:9], -1, 0
	s_cmp_gt_u32 s54, 6
	v_add_u32_e32 v117, s53, v102
	s_cbranch_scc1 .Lhg3_tail0
	global_load_dword v56, v240, s[82:83]
	global_load_ushort v84, v244, s[56:57]
	global_load_ushort v167, v242, s[82:83]
	global_load_dword v57, v240, s[82:83] offset:3072
	global_load_ushort v85, v245, s[56:57]
	global_load_ushort v166, v242, s[82:83] offset:3072
	global_load_dword v60, v241, s[82:83]
	global_load_ushort v107, v246, s[56:57]
	global_load_ushort v169, v243, s[82:83]
	global_load_dword v61, v241, s[82:83] offset:3072
	global_load_ushort v108, v247, s[56:57]
	global_load_ushort v168, v243, s[82:83] offset:3072
	v_add_u32_e32 v240, 0xc000, v240
	v_add_u32_e32 v241, 0xc000, v241
	v_add_u32_e32 v242, 0xc000, v242
	v_add_u32_e32 v243, 0xc000, v243
	v_add_u32_e32 v244, 0x26000, v244
	v_add_u32_e32 v245, 0x26000, v245
	v_add_u32_e32 v246, 0x26000, v246
	v_add_u32_e32 v247, 0x26000, v247
	s_branch .LBB0_363

.LBB0_363:
	s_waitcnt lgkmcnt(0)
	s_barrier
	ds_read_b128 v[40:43], v93 offset:4352
	ds_read_b128 v[118:121], v93
	ds_read2_b64 v[122:125], v100 offset1:4
	ds_read_b128 v[126:129], v93 offset:4416
	ds_read_b128 v[130:133], v93 offset:64
	ds_read_b128 v[134:137], v93 offset:4480
	v_cvt_pk_bf16_f32 v44, v36, v37
	v_cvt_pk_bf16_f32 v45, v38, v39
	v_cvt_pk_bf16_f32 v46, v32, v33
	s_waitcnt lgkmcnt(4)
	v_mfma_f32_16x16x32_bf16 v[40:43], v[40:43], v[118:121], 0
	v_cvt_pk_bf16_f32 v47, v34, v35
	ds_read2_b64 v[138:141], v100 offset0:8 offset1:12
	ds_read_b128 v[142:145], v93 offset:128
	ds_read_b128 v[158:161], v93 offset:4544
	v_cvt_pk_bf16_f32 v118, v28, v29
	s_waitcnt lgkmcnt(4)
	v_mfma_f32_16x16x32_bf16 v[40:43], v[126:129], v[130:133], v[40:43]
	ds_read_b128 v[130:133], v93 offset:192
	v_cvt_pk_bf16_f32 v119, v30, v31
	v_cvt_pk_bf16_f32 v120, v24, v25
	v_cvt_pk_bf16_f32 v121, v26, v27
	s_waitcnt lgkmcnt(2)
	v_mfma_f32_16x16x32_bf16 v[40:43], v[134:137], v[142:145], v[40:43]
	v_cvt_pk_bf16_f32 v126, v20, v21
	v_cvt_pk_bf16_f32 v127, v22, v23
	v_cvt_pk_bf16_f32 v128, v16, v17
	v_mfma_f32_16x16x32_bf16 v[44:47], v[44:47], v[122:125], 0
	v_cvt_pk_bf16_f32 v129, v18, v19
	ds_read2_b64 v[134:137], v100 offset0:16 offset1:20
	ds_read2_b64 v[122:125], v100 offset0:24 offset1:28
	s_waitcnt lgkmcnt(2)
	v_mfma_f32_16x16x32_bf16 v[40:43], v[158:161], v[130:133], v[40:43]
	v_cvt_pk_bf16_f32 v130, v12, v13
	v_cvt_pk_bf16_f32 v131, v14, v15
	v_cvt_pk_bf16_f32 v132, v8, v9
	v_mfma_f32_16x16x32_bf16 v[44:47], v[118:121], v[138:141], v[44:47]
	v_cvt_pk_bf16_f32 v133, v10, v11
	s_nop 2
	v_cndmask_b32_e64 v0, v40, 0, s[44:45]
	v_cndmask_b32_e64 v1, 0, v41, s[46:47]
	ds_read_b64 v[40:41], v94 offset:14848
	s_waitcnt lgkmcnt(2)
	v_mfma_f32_16x16x32_bf16 v[44:47], v[126:129], v[134:137], v[44:47]
	v_cndmask_b32_e64 v3, v42, 0, s[48:49]
	v_cndmask_b32_e64 v48, v43, 0, s[50:51]
	v_mov_b32_e32 v42, v2
	v_mov_b32_e32 v43, v2
	s_waitcnt lgkmcnt(1)
	v_mfma_f32_16x16x32_bf16 v[44:47], v[130:133], v[122:125], v[44:47]
	v_cvt_pk_bf16_f32 v0, v0, v1
	v_cvt_pk_bf16_f32 v1, v3, v48
	v_mov_b32_e32 v3, v2
	v_add_u32_e32 v118, v66, v96
	s_waitcnt lgkmcnt(0)
	v_mfma_f32_16x16x32_bf16 v[40:43], v[40:43], v[0:3], v[44:47]
	s_nop 2
	v_mov_b32_e32 v44, 0
	s_nop 3
	ds_write_b128 v95, v[40:43] offset:23552
	ds_read_b64 v[238:239], v174 offset:14848
	ds_read_b64 v[222:223], v175 offset:8704
	ds_read_b128 v[190:193], v97 offset:20992
	ds_read_b64 v[224:225], v175 offset:9472
	ds_read_b128 v[194:197], v97 offset:21056
	ds_read_b64 v[226:227], v175 offset:10240
	ds_read_b128 v[198:201], v97 offset:21120
	ds_read_b64 v[228:229], v175 offset:11008
	ds_read_b128 v[202:205], v97 offset:21184
	ds_read_b64 v[230:231], v175 offset:11776
	ds_read_b128 v[206:209], v97 offset:21248
	ds_read_b64 v[232:233], v175 offset:12544
	ds_read_b128 v[210:213], v97 offset:21312
	s_waitcnt lgkmcnt(10)
	v_pk_mul_f32 v[38:39], v[38:39], v[192:193]
	v_pk_mul_f32 v[36:37], v[36:37], v[190:191]
	s_nop 1
	v_mfma_f32_16x16x16_bf16 v[36:39], v[222:223], v[238:239], v[36:39]
	ds_read_b64 v[234:235], v175 offset:13312
	ds_read_b128 v[214:217], v97 offset:21376
	s_waitcnt lgkmcnt(10)
	v_pk_mul_f32 v[34:35], v[34:35], v[196:197]
	v_pk_mul_f32 v[32:33], v[32:33], v[194:195]
	s_nop 1
	v_mfma_f32_16x16x16_bf16 v[32:35], v[224:225], v[238:239], v[32:35]
	ds_read_b64 v[236:237], v175 offset:14080
	ds_read_b128 v[218:221], v97 offset:21440
	s_waitcnt lgkmcnt(10)
	v_pk_mul_f32 v[30:31], v[30:31], v[200:201]
	v_pk_mul_f32 v[28:29], v[28:29], v[198:199]
	s_nop 1
	v_mfma_f32_16x16x16_bf16 v[28:31], v[226:227], v[238:239], v[28:31]
	s_waitcnt lgkmcnt(8)
	v_pk_mul_f32 v[26:27], v[26:27], v[204:205]
	v_pk_mul_f32 v[24:25], v[24:25], v[202:203]
	s_nop 1
	v_mfma_f32_16x16x16_bf16 v[24:27], v[228:229], v[238:239], v[24:27]
	s_waitcnt lgkmcnt(6)
	v_pk_mul_f32 v[22:23], v[22:23], v[208:209]
	v_pk_mul_f32 v[20:21], v[20:21], v[206:207]
	s_nop 1
	v_mfma_f32_16x16x16_bf16 v[20:23], v[230:231], v[238:239], v[20:23]
	s_waitcnt lgkmcnt(4)
	v_pk_mul_f32 v[18:19], v[18:19], v[212:213]
	v_pk_mul_f32 v[16:17], v[16:17], v[210:211]
	s_nop 1
	v_mfma_f32_16x16x16_bf16 v[16:19], v[232:233], v[238:239], v[16:19]
	s_waitcnt lgkmcnt(2)
	v_pk_mul_f32 v[14:15], v[14:15], v[216:217]
	v_pk_mul_f32 v[12:13], v[12:13], v[214:215]
	s_nop 1
	v_mfma_f32_16x16x16_bf16 v[12:15], v[234:235], v[238:239], v[12:15]
	v_mov_b32_e32 v1, 0
	s_waitcnt lgkmcnt(0)
	s_barrier
	v_pk_mul_f32 v[10:11], v[10:11], v[220:221]
	v_pk_mul_f32 v[8:9], v[8:9], v[218:219]
	s_nop 1
	v_mfma_f32_16x16x16_bf16 v[8:11], v[236:237], v[238:239], v[8:11]
	ds_read_b128 v[40:43], v106 offset:23552
	s_waitcnt lgkmcnt(0)
	v_pk_mul_f32 v[44:45], v[42:43], v[42:43]
	v_pk_mul_f32 v[46:47], v[40:41], v[40:41]
	s_nop 0
	v_pk_mov_b32 v[48:49], v[46:47], v[44:45] op_sel:[1,0]
	v_mov_b32_e32 v47, v45
	v_pk_add_f32 v[44:45], v[48:49], v[46:47]
	s_nop 0
	v_add_f32_e32 v0, v44, v45
	s_waitcnt vmcnt(12)
	v_lshlrev_b32_e32 v44, 16, v80
	v_and_b32_e32 v45, 0xffff0000, v80
	v_add_f32_dpp v0, v0, v0 quad_perm:[1,0,3,2] row_mask:0xf bank_mask:0xf
	s_nop 1
	v_add_f32_dpp v0, v0, v0 quad_perm:[2,3,0,1] row_mask:0xf bank_mask:0xf
	s_nop 1
	v_add_f32_dpp v0, v0, v0 row_half_mirror row_mask:0xf bank_mask:0xf
	s_nop 1
	v_add_f32_dpp v0, v0, v0 row_mirror row_mask:0xf bank_mask:0xf
	v_mov_b32_e32 v3, v0
	s_nop 1
	v_permlane16_swap_b32_e32 v0, v3
	v_add_f32_e32 v0, v0, v3
	v_fmamk_f32 v0, v0, 0x3c000000, v178
	v_cmp_gt_f32_e32 vcc, s34, v0
	v_mul_f32_e32 v3, 0x4b800000, v0
	s_nop 0
	v_cndmask_b32_e32 v0, v0, v3, vcc
	v_rsq_f32_e32 v0, v0
	s_nop 0
	v_mul_f32_e32 v3, 0x45800000, v0
	v_cndmask_b32_e32 v0, v0, v3, vcc
	v_pk_mul_f32 v[40:41], v[40:41], v[0:1] op_sel_hi:[1,0]
	v_pk_mul_f32 v[42:43], v[42:43], v[0:1] op_sel_hi:[1,0]
	v_pk_mul_f32 v[40:41], v[4:5], v[40:41]
	v_pk_mul_f32 v[42:43], v[6:7], v[42:43]
	v_pk_mul_f32 v[40:41], v[40:41], v[44:45]
	v_lshlrev_b32_e32 v44, 16, v81
	v_and_b32_e32 v45, 0xffff0000, v81
	v_pk_mul_f32 v[42:43], v[42:43], v[44:45]
	v_cvt_pk_bf16_f32 v40, v40, v41
	v_cvt_pk_bf16_f32 v41, v42, v43
	v_lshlrev_b64 v[42:43], 11, v[78:79]
	v_lshl_add_u64 v[42:43], v[64:65], 0, v[42:43]
	v_add_u32_e32 v78, 16, v78
	global_store_dwordx2 v[42:43], v[40:41], off
	v_mad_i64_i32 v[40:41], s[0:1], v78, s30, v[68:69]
	global_load_dwordx2 v[80:81], v[40:41], off offset:1024
	v_sub_f32_e32 v0, 1.0, v58
	v_max_f32_e32 v112, 0xda24260, v0
	v_sub_f32_e32 v0, 1.0, v59
	v_max_f32_e32 v114, 0xda24260, v0
	v_sub_f32_e32 v0, 1.0, v62
	v_max_f32_e32 v115, 0xda24260, v0
	v_sub_f32_e32 v0, 1.0, v63
	v_max_f32_e32 v116, 0xda24260, v0
	v_lshlrev_b32_e32 v74, 16, v170
	v_lshlrev_b32_e32 v75, 16, v171
	v_lshlrev_b32_e32 v76, 16, v172
	v_lshlrev_b32_e32 v77, 16, v173
	v_log_f32_e32 v0, v112
	s_nop 0
	v_mul_f32_e32 v3, 0x3f317217, v0
	v_fma_f32 v3, v0, s97, -v3
	v_fmac_f32_e32 v3, 0x3377d1cf, v0
	v_fmac_f32_e32 v3, 0x3f317217, v0
	v_mov_b32_e32 v0, v3
	v_add_f32_e32 v47, 0, v0
	v_log_f32_e32 v0, v114
	s_nop 0
	v_mul_f32_e32 v3, 0x3f317217, v0
	v_fma_f32 v3, v0, s97, -v3
	v_fmac_f32_e32 v3, 0x3377d1cf, v0
	v_fmac_f32_e32 v3, 0x3f317217, v0
	v_mov_b32_e32 v0, v3
	v_add_f32_e32 v3, v0, v47
	v_log_f32_e32 v0, v115
	s_nop 0
	v_mul_f32_e32 v40, 0x3f317217, v0
	v_fma_f32 v40, v0, s97, -v40
	v_fmac_f32_e32 v40, 0x3377d1cf, v0
	v_fmac_f32_e32 v40, 0x3f317217, v0
	v_mov_b32_e32 v0, v40
	v_add_f32_e32 v46, v0, v3
	v_log_f32_e32 v0, v116
	s_nop 0
	v_mul_f32_e32 v40, 0x3f317217, v0
	v_fma_f32 v40, v0, s97, -v40
	v_fmac_f32_e32 v40, 0x3377d1cf, v0
	v_fmac_f32_e32 v40, 0x3f317217, v0
	v_mov_b32_e32 v0, v40
	v_add_f32_e32 v41, v0, v46
	ds_write_b32 v88, v41 offset:21504
	s_waitcnt lgkmcnt(0)
	s_barrier
	ds_read2st64_b32 v[42:43], v91 offset0:84 offset1:86
	ds_read2st64_b32 v[44:45], v91 offset0:88 offset1:90
	s_and_saveexec_b64 s[0:1], s[40:41]
	s_cbranch_execz .LBB0_389
	v_cmp_lt_i32_e32 vcc, 1, v83
	s_mov_b64 s[10:11], 0
	s_and_saveexec_b64 s[12:13], vcc
	s_xor_b64 s[12:13], exec, s[12:13]
	s_cbranch_execz .LBB0_413
	v_cmp_eq_u32_e32 vcc, 2, v83
	s_mov_b64 s[10:11], -1
	s_and_saveexec_b64 s[14:15], vcc
	s_cbranch_execz .LBB0_385
	s_waitcnt lgkmcnt(1)
	v_add_f32_e32 v1, v42, v43
	s_xor_b64 s[10:11], exec, -1

.LBB0_391:
	s_or_b64 exec, exec, s[0:1]
	s_andn2_b64 vcc, exec, s[8:9]
	s_cbranch_vccnz .Lhg3_tail1
	global_load_dword v58, v240, s[82:83]
	global_load_ushort v86, v244, s[56:57]
	global_load_ushort v171, v242, s[82:83]
	global_load_dword v59, v240, s[82:83] offset:3072
	global_load_ushort v89, v245, s[56:57]
	global_load_ushort v170, v242, s[82:83] offset:3072
	global_load_dword v62, v241, s[82:83]
	global_load_ushort v98, v246, s[56:57]
	global_load_ushort v173, v243, s[82:83]
	global_load_dword v63, v241, s[82:83] offset:3072
	global_load_ushort v101, v247, s[56:57]
	global_load_ushort v172, v243, s[82:83] offset:3072
	v_add_u32_e32 v240, 0xc000, v240
	v_add_u32_e32 v241, 0xc000, v241
	v_add_u32_e32 v242, 0xc000, v242
	v_add_u32_e32 v243, 0xc000, v243
	v_add_u32_e32 v244, 0x26000, v244
	v_add_u32_e32 v245, 0x26000, v245
	v_add_u32_e32 v246, 0x26000, v246
	v_add_u32_e32 v247, 0x26000, v247
	s_branch .LBB0_393
